# one-time S5 matrix expansion moved out of phase A0 into the tails of the two layer-0 in-projection GEMM phases (blocks without an 8th tile run one half each)
# speedup vs baseline: 1.0211x; 1.0090x over previous
; __global__ void __launch_bounds__(512, 2) fwd_kernel(KArgs a) {
;     ...
;             { const int la_ = (0), ha_ = (0); { const int l = la_, hf = ha_; (void)l; (void)hf;
;             for (int rep_ = 0; rep_ < REP_A; ++rep_) {
;             { IDS;
;             for (int row = gw; row < MH; row += NGW) {
;                 const bool isc = row >= ML; const int rr = isc ? row - ML : row;
;                 const float* xr = (isc ? xcin : xin) + (size_t)rr * 1024;
;                 const float* md = modl + (size_t)(isc ? 16 : hf * HB + (row >> 11)) * 3072;
;                 const float* ng = a.in[6] + l * 1024;
;                 f32x4 v[4]; float ss = 0.f;
; #pragma unroll
;                 for (int j = 0; j < 4; ++j) { v[j] = *(const f32x4*)(xr + 4 * lane + 256 * j); ss += (v[j][0] * v[j][0] + v[j][1] * v[j][1]) + (v[j][2] * v[j][2] + v[j][3] * v[j][3]); }
;                 const float rinv = rsqrtf(wave_sum(ss) * (1.f / 1024.f) + EPS);
.LBB0_143:
	s_or_b64 exec, exec, s[4:5]
	s_mov_b64 s[4:5], s[72:73]
	s_waitcnt lgkmcnt(0)
	s_barrier
	v_mov_b32 v1, v194
	s_mov_b64 s[6:7], exec
	s_branch .Lmy_pad_LBB0217
	s_nop 0
	s_nop 0
	s_nop 0
	s_nop 0
	s_nop 0
.Lmy_pad_LBB0217:
.LBB0_217:
	s_or_b64 exec, exec, s[6:7]
	s_mov_b64 s[4:5], s[72:73]
	v_mov_b32 v4, v194
	s_mov_b64 s[24:25], s[48:49]
	v_readfirstlane_b32 s6, v4
	s_ashr_i32 s6, s6, 6
	s_mov_b64 s[26:27], s[50:51]
	s_mov_b64 s[22:23], s[46:47]
	s_add_i32 s10, s6, s69
	v_readlane_b32 s36, v251, 56
	s_cmpk_lt_i32 s10, 0x4800
	v_mbcnt_lo_u32_b32 v12, -1, 0
	v_readlane_b32 s37, v251, 57
	v_readlane_b32 s40, v251, 60
	v_readlane_b32 s41, v251, 61
	v_readlane_b32 s48, v252, 4
	v_readlane_b32 s49, v252, 5
	v_readlane_b32 s50, v252, 6
	v_readlane_b32 s51, v252, 7
	v_readlane_b32 s38, v251, 58
	v_readlane_b32 s39, v251, 59
	v_readlane_b32 s42, v251, 62
	v_readlane_b32 s43, v251, 63
	v_readlane_b32 s44, v252, 0
	v_readlane_b32 s45, v252, 1
	v_readlane_b32 s46, v252, 2
	v_readlane_b32 s47, v252, 3
	s_cbranch_scc0 .LBB0_220
	v_lshlrev_b32_e32 v0, 2, v4
	v_and_b32_e32 v6, 0xfc, v0
	v_mbcnt_hi_u32_b32 v0, -1, v12
	v_and_b32_e32 v2, 64, v0
	v_add_u32_e32 v2, 64, v2
	v_xor_b32_e32 v3, 1, v0
	v_cmp_lt_i32_e32 vcc, v3, v2
	s_ashr_i32 s7, s6, 31
	s_ashr_i32 s8, s69, 31
	v_cndmask_b32_e32 v3, v0, v3, vcc
	v_lshlrev_b32_e32 v13, 2, v3
	v_xor_b32_e32 v3, 2, v0
	v_cmp_lt_i32_e32 vcc, v3, v2
	s_add_u32 s6, s6, s69
	s_mov_b64 s[66:67], s[50:51]
	v_cndmask_b32_e32 v3, v0, v3, vcc
	v_lshlrev_b32_e32 v14, 2, v3
	v_xor_b32_e32 v3, 4, v0
	v_cmp_lt_i32_e32 vcc, v3, v2
	s_addc_u32 s7, s7, s8
	s_mov_b64 s[64:65], s[48:49]
	v_cndmask_b32_e32 v3, v0, v3, vcc
	v_lshlrev_b32_e32 v15, 2, v3
	v_xor_b32_e32 v3, 8, v0
	v_cmp_lt_i32_e32 vcc, v3, v2
	v_mov_b32_e32 v1, 0
	s_lshl_b64 s[6:7], s[6:7], 11
	v_cndmask_b32_e32 v3, v0, v3, vcc
	v_lshlrev_b32_e32 v16, 2, v3
	v_xor_b32_e32 v3, 16, v0
	v_cmp_lt_i32_e32 vcc, v3, v2
	s_add_u32 s6, s4, s6
	s_addc_u32 s7, s5, s7
	v_cndmask_b32_e32 v3, v0, v3, vcc
	v_lshlrev_b32_e32 v17, 2, v3
	v_xor_b32_e32 v3, 32, v0
	v_cmp_lt_i32_e32 vcc, v3, v2
	v_or_b32_e32 v8, 0x100, v6
	v_or_b32_e32 v10, 0x200, v6
	v_cndmask_b32_e32 v0, v0, v3, vcc
	v_lshlrev_b32_e32 v18, 2, v0
	v_lshlrev_b32_e32 v0, 2, v6
	v_lshl_add_u64 v[2:3], s[64:65], 0, v[0:1]
	v_and_b32_e32 v0, 63, v4
	v_lshlrev_b32_e32 v0, 3, v0
	v_or_b32_e32 v20, 0x300, v6
	v_lshl_add_u64 v[4:5], s[6:7], 0, v[0:1]
	s_mov_b64 s[6:7], 0x46b8000
	s_ashr_i32 s61, s60, 31
	s_mov_b64 s[52:53], s[36:37]
	s_mov_b64 s[56:57], s[40:41]
	v_lshl_add_u64 v[4:5], v[4:5], 0, s[6:7]
	s_lshl_b64 s[6:7], s[60:61], 11
	v_lshlrev_b32_e32 v0, 2, v6
	v_mov_b32_e32 v19, 0x358637bd
	s_mov_b32 s11, 0x800000
	v_lshlrev_b32_e32 v6, 2, v8
	v_mov_b32_e32 v7, v1
	v_lshlrev_b32_e32 v8, 2, v10
	v_mov_b32_e32 v9, v1
	v_lshlrev_b32_e32 v10, 2, v20
	v_mov_b32_e32 v11, v1

; __device__ __forceinline__ unsigned cvt_pk_bf16(float lo, float hi) { unsigned r; asm volatile("v_cvt_pk_bf16_f32 %0, %1, %2" : "=v"(r) : "v"(lo), "v"(hi)); return r; }
; __global__ void __launch_bounds__(512, 2) fwd_kernel(KArgs a) {
;     ...
;                 for (int t = gt; t < 2 * 16 * 256 * 64; t += NGT) {
;                     const int kc = t & 63, n = (t >> 6) & 255, g = (t >> 14) & 15, ll = t >> 18;
;                     const int d = n >> 7, ri = (n >> 6) & 1, p = n & 63, k0 = kc * 8, sp = k0 >> 4, j0 = k0 & 15, e = d == 0 ? 31 - sp : sp;
;                     const float* pw = POW + ((size_t)(((ll * 2 + d) * 16 + g) * 33 + e) * 64 + p) * 2; const float pr = pw[0], pi = pw[1];
;                     const float* bb = BBAR + (((size_t)((ll * 2 + d) * 16 + g) * 64 + p) * 16 + j0) * 2; float v[8];
; #pragma unroll
;                     for (int j = 0; j < 8; ++j) { const float br = bb[2 * j], bi = bb[2 * j + 1]; v[j] = ri == 0 ? pr * br - pi * bi : pr * bi + pi * br; }
;                     u32x4 o; o.x = cvt_pk_bf16(v[0], v[1]); o.y = cvt_pk_bf16(v[2], v[3]); o.z = cvt_pk_bf16(v[4], v[5]); o.w = cvt_pk_bf16(v[6], v[7]);
;                     *(u32x4*)(WEND + ((size_t)(ll * 16 + g) * 256 + n) * 512 + k0) = o;
;                 }
;                 for (int t = gt; t < 2 * 16 * 512 * 96; t += NGT) {
;                     const int kc = t % 96, n = (t / 96) & 511, g = (t / (96 * 512)) & 15, ll = t / (96 * 512 * 16);
.LBB0_365:
	v_readlane_b32 s36, v254, 14
	v_readlane_b32 s20, v250, 23
	s_cmp_lg_u32 s36, 0
	s_cbranch_scc1 .Lmy_exp_skip
	s_lshl_b32 s21, s20, 18
	s_add_i32 s78, s21, 0x40000
	s_mul_i32 s79, s20, 0xc0000
	s_add_i32 s1, s79, 0xc0000
	s_cmp_lt_u32 s91, 8
	s_cbranch_scc1 .Lmy_exp_skip
	s_sub_i32 s64, s91, 8
	s_sub_i32 s65, s74, 8
	s_lshl_b32 s44, s64, 9
	s_lshl_b32 s46, s65, 9
	v_readlane_b32 s22, v251, 30
	v_readlane_b32 s23, v251, 31
	v_readlane_b32 s24, v251, 32
	v_readlane_b32 s25, v251, 33
	s_mov_b64 s[36:37], s[72:73]
	v_mov_b32_e32 v61, v194
	s_mov_b32 s38, s78
	v_add_u32_e32 v60, s44, v61
	v_add_u32_e32 v60, s21, v60
	v_cmp_gt_i32_e32 vcc, s38, v60
	s_and_saveexec_b64 s[38:39], vcc
	s_cbranch_execz .Lmy_exp_146
	s_add_u32 s40, s36, 0x2330000
	s_addc_u32 s41, s37, 0
	s_add_u32 s42, s36, 0x2438000
	s_addc_u32 s43, s37, 0
	s_add_u32 s52, s36, 0x26b8000
	v_lshlrev_b32_e32 v61, 3, v61
	s_addc_u32 s53, s37, 0
	v_lshl_add_u32 v61, s64, 12, v61
	s_lshl_b32 s45, s65, 12
	s_mov_b64 s[54:55], 0
	s_movk_i32 s48, 0x80
	v_mov_b32_e32 v63, 0
	s_add_i32 s56, s78, -1
	v_mov_b32_e32 v64, v60
.Lmy_exp_145:
	v_bfe_u32 v65, v64, 6, 8
	v_ashrrev_i32_e32 v85, 18, v64
	v_bfe_u32 v67, v61, 4, 5
	v_lshrrev_b32_e32 v62, 9, v64
	v_bfe_u32 v84, v64, 14, 4
	v_bfe_u32 v66, v64, 6, 6
	v_xor_b32_e32 v68, 31, v67
	v_lshlrev_b32_e32 v69, 5, v85
	v_and_b32_e32 v71, 16, v62
	v_cmp_gt_u32_e32 vcc, s48, v65
	v_lshlrev_b32_e32 v62, 3, v66
	v_lshlrev_b32_e32 v72, 4, v66
	v_cndmask_b32_e32 v67, v67, v68, vcc
	v_or3_b32 v66, v69, v71, v84
	v_mad_i32_i24 v68, v66, 33, v67
	v_ashrrev_i32_e32 v67, 31, v66
	v_ashrrev_i32_e32 v69, 31, v68
	v_and_b32_e32 v70, 8, v61
	v_lshlrev_b64 v[66:67], 10, v[66:67]
	v_lshlrev_b64 v[68:69], 9, v[68:69]
	v_or3_b32 v66, v66, v72, v70
	v_lshl_add_u64 v[68:69], s[40:41], 0, v[68:69]
	v_lshl_add_u64 v[78:79], v[66:67], 3, s[42:43]
	v_lshl_add_u64 v[80:81], v[68:69], 0, v[62:63]
	flat_load_dwordx4 v[66:69], v[78:79] offset:16
	flat_load_dwordx4 v[70:73], v[78:79] offset:32
	flat_load_dwordx4 v[74:77], v[78:79] offset:48
	flat_load_dwordx2 v[82:83], v[80:81]
	s_nop 0
	flat_load_dwordx4 v[78:81], v[78:79]
	v_lshl_or_b32 v84, v85, 4, v84
	v_ashrrev_i32_e32 v85, 31, v84
	v_and_b32_e32 v102, 0x1000, v64
	v_add_u32_e32 v64, s46, v64
	v_lshlrev_b64 v[84:85], 18, v[84:85]
	v_and_b32_e32 v86, 0x1f8, v61
	v_cmp_lt_i32_e32 vcc, s56, v64
	v_lshl_add_u64 v[84:85], s[52:53], 0, v[84:85]
	v_lshlrev_b32_e32 v62, 10, v65
	s_or_b64 s[54:55], vcc, s[54:55]
	v_lshl_add_u64 v[84:85], v[84:85], 0, v[62:63]
	v_lshlrev_b32_e32 v62, 1, v86
	v_cmp_eq_u32_e32 vcc, 0, v102
	v_add_u32_e32 v61, s45, v61
	v_lshl_add_u64 v[84:85], v[84:85], 0, v[62:63]
	s_waitcnt vmcnt(0) lgkmcnt(0)
	v_pk_mul_f32 v[90:91], v[82:83], v[66:67]
	v_pk_mul_f32 v[66:67], v[82:83], v[66:67] op_sel:[1,0] op_sel_hi:[0,1]
	v_pk_mul_f32 v[92:93], v[82:83], v[68:69]
	v_pk_mul_f32 v[68:69], v[82:83], v[68:69] op_sel:[1,0] op_sel_hi:[0,1]
	v_pk_mul_f32 v[94:95], v[82:83], v[70:71]
	v_pk_mul_f32 v[70:71], v[82:83], v[70:71] op_sel:[1,0] op_sel_hi:[0,1]
	v_pk_mul_f32 v[96:97], v[82:83], v[72:73]
	v_pk_mul_f32 v[72:73], v[82:83], v[72:73] op_sel:[1,0] op_sel_hi:[0,1]
	v_pk_mul_f32 v[86:87], v[82:83], v[78:79]
	v_pk_mul_f32 v[78:79], v[82:83], v[78:79] op_sel:[1,0] op_sel_hi:[0,1]
	v_pk_mul_f32 v[88:89], v[82:83], v[80:81]
	v_pk_mul_f32 v[80:81], v[82:83], v[80:81] op_sel:[1,0] op_sel_hi:[0,1]
	v_pk_mul_f32 v[98:99], v[82:83], v[74:75]
	v_pk_mul_f32 v[74:75], v[82:83], v[74:75] op_sel:[1,0] op_sel_hi:[0,1]
	v_pk_mul_f32 v[100:101], v[82:83], v[76:77]
	v_pk_mul_f32 v[76:77], v[82:83], v[76:77] op_sel:[1,0] op_sel_hi:[0,1]
	v_add_f32_e32 v66, v66, v67
	v_sub_f32_e32 v67, v92, v93
	v_add_f32_e32 v68, v68, v69
	v_sub_f32_e32 v69, v94, v95
	v_add_f32_e32 v70, v70, v71
	v_sub_f32_e32 v71, v96, v97
	v_add_f32_e32 v72, v72, v73
	v_sub_f32_e32 v62, v86, v87
	v_add_f32_e32 v65, v78, v79
	v_sub_f32_e32 v78, v88, v89
	v_add_f32_e32 v79, v80, v81
	v_sub_f32_e32 v80, v90, v91
	v_sub_f32_e32 v73, v98, v99
	v_add_f32_e32 v74, v74, v75
	v_sub_f32_e32 v75, v100, v101
	v_add_f32_e32 v76, v76, v77
	v_cndmask_b32_e32 v67, v68, v67, vcc
	v_cndmask_b32_e32 v68, v70, v69, vcc
	v_cndmask_b32_e32 v69, v72, v71, vcc
	v_cndmask_b32_e32 v62, v65, v62, vcc
	v_cndmask_b32_e32 v65, v79, v78, vcc
	v_cndmask_b32_e32 v77, v66, v80, vcc
	v_cndmask_b32_e32 v70, v74, v73, vcc
	v_cndmask_b32_e32 v71, v76, v75, vcc
	v_cvt_pk_bf16_f32 v66, v62, v65
	v_cvt_pk_bf16_f32 v67, v77, v67
	v_cvt_pk_bf16_f32 v68, v68, v69
	v_cvt_pk_bf16_f32 v69, v70, v71
	flat_store_dwordx4 v[84:85], v[66:69]
	s_andn2_b64 exec, exec, s[54:55]
	s_cbranch_execnz .Lmy_exp_145
.Lmy_exp_146:
	s_or_b64 exec, exec, s[38:39]
	v_subrev_u32_e32 v60, s21, v60
	v_add_u32_e32 v60, s79, v60
	s_mov_b32 s38, s1
	v_cmp_gt_i32_e32 vcc, s38, v60
	s_and_saveexec_b64 s[38:39], vcc
	s_cbranch_execz .Lmy_exp_217
	s_add_u32 s40, s36, 0x2330000
	s_addc_u32 s41, s37, 0
	s_add_u32 s42, s36, 0x24b8000
	s_addc_u32 s43, s37, 0
	s_add_u32 s52, s36, 0x2eb8000
	s_addc_u32 s53, s37, 0
	v_lshlrev_b32_e32 v62, 3, v60
	s_lshl_b32 s45, s46, 3
	s_mov_b64 s[54:55], 0
	s_movk_i32 s48, 0x80
	v_mov_b32_e32 v65, 0
	s_movk_i32 s51, 0x600
	s_add_i32 s61, s1, -1
	s_branch .Lmy_exp_150

; __device__ __forceinline__ unsigned cvt_pk_bf16(float lo, float hi) { unsigned r; asm volatile("v_cvt_pk_bf16_f32 %0, %1, %2" : "=v"(r) : "v"(lo), "v"(hi)); return r; }
; __global__ void __launch_bounds__(512, 2) fwd_kernel(KArgs a) {
;     ...
;                 for (int t = gt; t < 2 * 16 * 512 * 96; t += NGT) {
;                     const int kc = t % 96, n = (t / 96) & 511, g = (t / (96 * 512)) & 15, ll = t / (96 * 512 * 16);
;                     const int s = n >> 4, i = n & 15, k0 = kc * 8; float v[8];
;                     if (k0 < 512) { const int sp = k0 >> 4, j0 = k0 & 15;
;                         const float* kf = KT + ((size_t)((ll * 16 + g) * 2 + 0) * 32) * 256 + i * 16 + j0; const float* kb = KT + ((size_t)((ll * 16 + g) * 2 + 1) * 32) * 256 + i * 16 + j0;
; #pragma unroll
;                         for (int j = 0; j < 8; ++j) v[j] = sp < s ? kf[(size_t)(s - sp) * 256 + j] : (sp > s ? kb[(size_t)(sp - s) * 256 + j] : kf[j] + kb[j]);
;                     } else { const int kk = k0 - 512, d = kk >> 7, ri = (kk >> 6) & 1, p0 = kk & 63, e = d == 0 ? s + 1 : 32 - s;
;                         const float* pw = POW + ((size_t)(((ll * 2 + d) * 16 + g) * 33 + e) * 64 + p0) * 2;
;                         const size_t ic = ((size_t)((ll * 2 + d) * 16 + g) * 16 + i) * 64 + p0;
; #pragma unroll
;                         for (int j = 0; j < 8; ++j) { const float cr = a.in[19][ic + j], ci = a.in[20][ic + j], pr = pw[2 * j], pi = pw[2 * j + 1];
;                             v[j] = ri == 0 ? cr * pr - ci * pi : -(cr * pi + ci * pr); }
;                     }
;                     u32x4 o; o.x = cvt_pk_bf16(v[0], v[1]); o.y = cvt_pk_bf16(v[2], v[3]); o.z = cvt_pk_bf16(v[4], v[5]); o.w = cvt_pk_bf16(v[6], v[7]);
;                     *(u32x4*)(BM2 + ((size_t)(ll * 16 + g) * 512 + n) * 768 + k0) = o;
.Lmy_exp_149:
	s_or_b64 exec, exec, s[56:57]
	v_and_b32_e32 v64, 0x1ff, v76
	v_lshlrev_b32_e32 v61, 9, v61
	v_lshlrev_b32_e32 v63, 13, v63
	v_or3_b32 v61, v63, v61, v64
	v_mov_b64_e32 v[72:73], s[52:53]
	v_add_u32_e32 v60, s46, v60
	s_waitcnt vmcnt(0) lgkmcnt(0)
	v_cvt_pk_bf16_f32 v68, v67, v77
	v_mad_i64_i32 v[72:73], s[36:37], v61, s51, v[72:73]
	v_ashrrev_i32_e32 v67, 31, v66
	v_cmp_lt_i32_e32 vcc, s61, v60
	v_lshl_add_u64 v[66:67], v[66:67], 1, v[72:73]
	s_or_b64 s[54:55], vcc, s[54:55]
	v_add_u32_e32 v62, s45, v62
	v_cvt_pk_bf16_f32 v69, v78, v79
	v_cvt_pk_bf16_f32 v70, v80, v81
	v_cvt_pk_bf16_f32 v71, v82, v83
	flat_store_dwordx4 v[66:67], v[68:71]
	s_andn2_b64 exec, exec, s[54:55]
	s_cbranch_execz .Lmy_exp_217
.Lmy_exp_150:
	s_mov_b32 s36, 0x2aaaaaab
	v_mul_hi_i32 v63, v60, s36
	v_ashrrev_i32_e32 v61, 4, v63
	v_lshrrev_b32_e32 v64, 31, v63
	v_add_u32_e32 v76, v61, v64
	s_movk_i32 s36, 0xffa0
	v_mad_u64_u32 v[68:69], s[36:37], v76, s36, v[60:61]
	v_lshrrev_b32_e32 v61, 13, v63
	v_ashrrev_i32_e32 v63, 17, v63
	v_add_u32_e32 v61, v61, v64
	v_add_u32_e32 v63, v63, v64
	v_and_b32_e32 v64, 15, v76
	s_movk_i32 s36, 0xfd00
	v_and_b32_e32 v61, 15, v61
	v_bfe_u32 v74, v76, 4, 5
	v_mad_u64_u32 v[66:67], s[36:37], v76, s36, v[62:63]
	v_cmp_lt_i32_e32 vcc, 63, v68
	v_lshlrev_b32_e32 v64, 6, v64
	s_and_saveexec_b64 s[36:37], vcc
	s_xor_b64 s[36:37], exec, s[36:37]
	s_cbranch_execz .Lmy_exp_152
	v_add_u32_e32 v67, 0xfffffe00, v66
	v_cmp_gt_u32_e32 vcc, s48, v67
	v_lshrrev_b32_e32 v67, 3, v67
	v_and_b32_e32 v67, 0x1ffffff0, v67
	v_add_u32_e32 v70, 1, v74
	v_sub_u32_e32 v71, 32, v74
	v_lshl_add_u32 v67, v63, 5, v67
	v_cndmask_b32_e32 v70, v71, v70, vcc
	v_or_b32_e32 v72, v67, v61
	v_mad_u64_u32 v[70:71], s[56:57], v72, 33, v[70:71]
	v_ashrrev_i32_e32 v71, 31, v70
	v_and_b32_e32 v69, 56, v66
	v_lshlrev_b64 v[70:71], 9, v[70:71]
	v_ashrrev_i32_e32 v73, 31, v72
	v_lshl_add_u64 v[70:71], s[40:41], 0, v[70:71]
	v_lshlrev_b32_e32 v74, 3, v69
	v_mov_b32_e32 v75, v65
	v_lshlrev_b64 v[78:79], 10, v[72:73]
	v_lshl_add_u64 v[74:75], v[70:71], 0, v[74:75]
	v_or3_b32 v78, v78, v64, v69
	flat_load_dwordx4 v[70:73], v[74:75]
	v_lshlrev_b64 v[78:79], 2, v[78:79]
	v_lshl_add_u64 v[102:103], s[22:23], 0, v[78:79]
	v_lshl_add_u64 v[98:99], s[24:25], 0, v[78:79]
	global_load_dwordx4 v[78:81], v[98:99], off
	global_load_dwordx4 v[82:85], v[102:103], off
	flat_load_dwordx4 v[86:89], v[74:75] offset:16
	flat_load_dwordx4 v[90:93], v[74:75] offset:32
	flat_load_dwordx4 v[94:97], v[74:75] offset:48
	s_nop 0
	global_load_dwordx4 v[98:101], v[98:99], off offset:16
	s_nop 0
	global_load_dwordx4 v[102:105], v[102:103], off offset:16
	v_and_b32_e32 v64, 8, v68
	v_cmp_eq_u32_e32 vcc, 0, v64
	s_waitcnt vmcnt(0)
	v_mov_b32_e32 v106, v78
	v_mov_b32_e32 v107, v83
	s_waitcnt lgkmcnt(0)
	v_mov_b32_e32 v69, v72
	v_mov_b32_e32 v75, v72
	v_mov_b32_e32 v72, v71
	v_mov_b32_e32 v68, v71
	v_mov_b32_e32 v74, v70
	v_mov_b32_e32 v71, v73
	v_mov_b32_e32 v109, v88
	v_mov_b32_e32 v88, v87
	v_mov_b32_e32 v87, v92
	v_mov_b32_e32 v92, v91
	v_mov_b32_e32 v91, v96
	v_mov_b32_e32 v96, v95
	v_pk_mul_f32 v[72:73], v[78:79], v[72:73]
	v_mov_b32_e32 v108, v86
	v_mov_b32_e32 v86, v90
	v_mov_b32_e32 v90, v94
	v_pk_mul_f32 v[70:71], v[106:107], v[70:71]
	v_pk_mul_f32 v[94:95], v[80:81], v[88:89]
	v_pk_mul_f32 v[88:89], v[84:85], v[88:89]
	v_pk_mul_f32 v[106:107], v[98:99], v[92:93]
	v_pk_mul_f32 v[92:93], v[102:103], v[92:93]
	v_pk_mul_f32 v[110:111], v[100:101], v[96:97]
	v_pk_mul_f32 v[96:97], v[104:105], v[96:97]
	v_pk_fma_f32 v[72:73], v[82:83], v[74:75], v[72:73] neg_lo:[0,0,1] neg_hi:[0,0,1]
	v_mov_b32_e32 v83, v79
	v_pk_fma_f32 v[74:75], v[84:85], v[108:109], v[94:95] neg_lo:[0,0,1] neg_hi:[0,0,1]
	v_pk_fma_f32 v[78:79], v[80:81], v[108:109], v[88:89]
	v_pk_fma_f32 v[80:81], v[102:103], v[86:87], v[106:107] neg_lo:[0,0,1] neg_hi:[0,0,1]
	v_pk_fma_f32 v[84:85], v[98:99], v[86:87], v[92:93]
	v_pk_fma_f32 v[86:87], v[104:105], v[90:91], v[110:111] neg_lo:[0,0,1] neg_hi:[0,0,1]
	v_pk_fma_f32 v[88:89], v[100:101], v[90:91], v[96:97]
	v_pk_fma_f32 v[68:69], v[82:83], v[68:69], v[70:71]
	v_cndmask_b32_e64 v78, -v78, v74, vcc
	v_cndmask_b32_e64 v67, -v68, v72, vcc
	v_cndmask_b32_e64 v77, -v69, v73, vcc
	v_cndmask_b32_e64 v79, -v79, v75, vcc
	v_cndmask_b32_e64 v80, -v84, v80, vcc
	v_cndmask_b32_e64 v81, -v85, v81, vcc
	v_cndmask_b32_e64 v82, -v88, v86, vcc
	v_cndmask_b32_e64 v83, -v89, v87, vcc
; __global__ void __launch_bounds__(512, 2) fwd_kernel(KArgs a) {
;     ...
;                     if (k0 < 512) { const int sp = k0 >> 4, j0 = k0 & 15;
;                         const float* kf = KT + ((size_t)((ll * 16 + g) * 2 + 0) * 32) * 256 + i * 16 + j0; const float* kb = KT + ((size_t)((ll * 16 + g) * 2 + 1) * 32) * 256 + i * 16 + j0;
; #pragma unroll
;                         for (int j = 0; j < 8; ++j) v[j] = sp < s ? kf[(size_t)(s - sp) * 256 + j] : (sp > s ? kb[(size_t)(sp - s) * 256 + j] : kf[j] + kb[j]);
.Lmy_exp_152:
	s_andn2_saveexec_b64 s[56:57], s[36:37]
	s_cbranch_execz .Lmy_exp_149
	v_ashrrev_i32_e32 v75, 1, v68
	v_lshlrev_b32_e32 v68, 5, v63
	v_lshl_or_b32 v70, v61, 1, v68
	v_ashrrev_i32_e32 v71, 31, v70
	v_lshlrev_b64 v[68:69], 15, v[70:71]
	v_or_b32_e32 v70, 1, v70
	v_ashrrev_i32_e32 v71, 31, v70
	v_lshlrev_b64 v[70:71], 15, v[70:71]
	v_and_b32_e32 v67, 8, v66
	v_lshl_add_u64 v[68:69], s[42:43], 0, v[68:69]
	v_lshl_add_u64 v[70:71], s[42:43], 0, v[70:71]
	v_lshl_add_u64 v[68:69], v[68:69], 0, v[64:65]
	v_lshlrev_b32_e32 v72, 2, v67
	v_mov_b32_e32 v73, v65
	v_lshl_add_u64 v[70:71], v[70:71], 0, v[64:65]
	v_sub_u32_e32 v64, v75, v74
	v_lshl_add_u64 v[68:69], v[68:69], 0, v[72:73]
	v_lshl_add_u64 v[72:73], v[70:71], 0, v[72:73]
	v_lshlrev_b64 v[70:71], 10, v[64:65]
	v_cmp_ge_i32_e64 s[36:37], v75, v74
	v_cmp_le_i32_e32 vcc, v75, v74
	v_lshl_add_u64 v[70:71], v[72:73], 0, v[70:71]
	s_and_saveexec_b64 s[58:59], s[36:37]
	s_xor_b64 s[58:59], exec, s[58:59]
	s_cbranch_execz .Lmy_exp_159
	s_and_saveexec_b64 s[18:19], vcc
	s_xor_b64 s[18:19], exec, s[18:19]
	s_cbranch_execz .Lmy_exp_156
	flat_load_dword v64, v[68:69]
	flat_load_dword v67, v[72:73]
	s_waitcnt vmcnt(0) lgkmcnt(0)
	v_add_f32_e32 v67, v64, v67
.Lmy_exp_156:
	s_andn2_saveexec_b64 s[18:19], s[18:19]
	s_cbranch_execz .Lmy_exp_158
	flat_load_dword v67, v[70:71]
.Lmy_exp_158:
	s_or_b64 exec, exec, s[18:19]
.Lmy_exp_159:
	s_or_saveexec_b64 s[58:59], s[58:59]
	v_sub_u32_e32 v64, v74, v75
	v_lshlrev_b64 v[74:75], 10, v[64:65]
	v_lshl_add_u64 v[74:75], v[68:69], 0, v[74:75]
	s_xor_b64 exec, exec, s[58:59]
	s_cbranch_execz .Lmy_exp_161
	s_waitcnt vmcnt(0) lgkmcnt(0)
	flat_load_dword v67, v[74:75]
.Lmy_exp_161:
	s_or_b64 exec, exec, s[58:59]
	s_and_saveexec_b64 s[58:59], s[36:37]
	s_xor_b64 s[58:59], exec, s[58:59]
	s_cbranch_execz .Lmy_exp_167
	s_and_saveexec_b64 s[18:19], vcc
	s_xor_b64 s[18:19], exec, s[18:19]
	s_cbranch_execz .Lmy_exp_164
	flat_load_dword v64, v[68:69] offset:4
	flat_load_dword v77, v[72:73] offset:4
	s_waitcnt vmcnt(0) lgkmcnt(0)
	v_add_f32_e32 v77, v64, v77
.Lmy_exp_164:
	s_andn2_saveexec_b64 s[18:19], s[18:19]
	s_cbranch_execz .Lmy_exp_166
	flat_load_dword v77, v[70:71] offset:4
.Lmy_exp_166:
	s_or_b64 exec, exec, s[18:19]
	s_andn2_saveexec_b64 s[58:59], s[58:59]
	s_cbranch_execz .Lmy_exp_169
	s_branch .Lmy_exp_168
.Lmy_exp_167:
	s_andn2_saveexec_b64 s[58:59], s[58:59]
	s_cbranch_execz .Lmy_exp_169
.Lmy_exp_168:
	s_waitcnt vmcnt(0) lgkmcnt(0)
	flat_load_dword v77, v[74:75] offset:4
.Lmy_exp_169:
	s_or_b64 exec, exec, s[58:59]
	s_and_saveexec_b64 s[58:59], s[36:37]
	s_xor_b64 s[58:59], exec, s[58:59]
	s_cbranch_execz .Lmy_exp_175
	s_and_saveexec_b64 s[18:19], vcc
	s_xor_b64 s[18:19], exec, s[18:19]
	s_cbranch_execz .Lmy_exp_172
	flat_load_dword v64, v[68:69] offset:8
	flat_load_dword v78, v[72:73] offset:8
	s_waitcnt vmcnt(0) lgkmcnt(0)
	v_add_f32_e32 v78, v64, v78
.Lmy_exp_172:
	s_andn2_saveexec_b64 s[18:19], s[18:19]
	s_cbranch_execz .Lmy_exp_174
	flat_load_dword v78, v[70:71] offset:8

; __global__ void __launch_bounds__(512, 2) fwd_kernel(KArgs a) {
;     ...
;                         const float* kf = KT + ((size_t)((ll * 16 + g) * 2 + 0) * 32) * 256 + i * 16 + j0; const float* kb = KT + ((size_t)((ll * 16 + g) * 2 + 1) * 32) * 256 + i * 16 + j0;
; #pragma unroll
;                         for (int j = 0; j < 8; ++j) v[j] = sp < s ? kf[(size_t)(s - sp) * 256 + j] : (sp > s ? kb[(size_t)(sp - s) * 256 + j] : kf[j] + kb[j]);
.Lmy_exp_176:
	s_waitcnt vmcnt(0) lgkmcnt(0)
	flat_load_dword v78, v[74:75] offset:8
.Lmy_exp_177:
	s_or_b64 exec, exec, s[58:59]
	s_and_saveexec_b64 s[58:59], s[36:37]
	s_xor_b64 s[58:59], exec, s[58:59]
	s_cbranch_execz .Lmy_exp_183
	s_and_saveexec_b64 s[18:19], vcc
	s_xor_b64 s[18:19], exec, s[18:19]
	s_cbranch_execz .Lmy_exp_180
	flat_load_dword v64, v[68:69] offset:12
	flat_load_dword v79, v[72:73] offset:12
	s_waitcnt vmcnt(0) lgkmcnt(0)
	v_add_f32_e32 v79, v64, v79
.Lmy_exp_180:
	s_andn2_saveexec_b64 s[18:19], s[18:19]
	s_cbranch_execz .Lmy_exp_182
	flat_load_dword v79, v[70:71] offset:12

; __global__ void __launch_bounds__(512, 2) fwd_kernel(KArgs a) {
;     ...
;                         const float* kf = KT + ((size_t)((ll * 16 + g) * 2 + 0) * 32) * 256 + i * 16 + j0; const float* kb = KT + ((size_t)((ll * 16 + g) * 2 + 1) * 32) * 256 + i * 16 + j0;
; #pragma unroll
;                         for (int j = 0; j < 8; ++j) v[j] = sp < s ? kf[(size_t)(s - sp) * 256 + j] : (sp > s ? kb[(size_t)(sp - s) * 256 + j] : kf[j] + kb[j]);
.Lmy_exp_184:
	s_waitcnt vmcnt(0) lgkmcnt(0)
	flat_load_dword v79, v[74:75] offset:12
.Lmy_exp_185:
	s_or_b64 exec, exec, s[58:59]
	s_and_saveexec_b64 s[58:59], s[36:37]
	s_xor_b64 s[58:59], exec, s[58:59]
	s_cbranch_execz .Lmy_exp_191
	s_and_saveexec_b64 s[18:19], vcc
	s_xor_b64 s[18:19], exec, s[18:19]
	s_cbranch_execz .Lmy_exp_188
	flat_load_dword v64, v[68:69] offset:16
	flat_load_dword v80, v[72:73] offset:16
	s_waitcnt vmcnt(0) lgkmcnt(0)
	v_add_f32_e32 v80, v64, v80
.Lmy_exp_188:
	s_andn2_saveexec_b64 s[18:19], s[18:19]
	s_cbranch_execz .Lmy_exp_190
	flat_load_dword v80, v[70:71] offset:16

; __global__ void __launch_bounds__(512, 2) fwd_kernel(KArgs a) {
;     ...
;                         const float* kf = KT + ((size_t)((ll * 16 + g) * 2 + 0) * 32) * 256 + i * 16 + j0; const float* kb = KT + ((size_t)((ll * 16 + g) * 2 + 1) * 32) * 256 + i * 16 + j0;
; #pragma unroll
;                         for (int j = 0; j < 8; ++j) v[j] = sp < s ? kf[(size_t)(s - sp) * 256 + j] : (sp > s ? kb[(size_t)(sp - s) * 256 + j] : kf[j] + kb[j]);
.Lmy_exp_192:
	s_waitcnt vmcnt(0) lgkmcnt(0)
	flat_load_dword v80, v[74:75] offset:16
.Lmy_exp_193:
	s_or_b64 exec, exec, s[58:59]
	s_and_saveexec_b64 s[58:59], s[36:37]
	s_xor_b64 s[58:59], exec, s[58:59]
	s_cbranch_execz .Lmy_exp_199
	s_and_saveexec_b64 s[18:19], vcc
	s_xor_b64 s[18:19], exec, s[18:19]
	s_cbranch_execz .Lmy_exp_196
	flat_load_dword v64, v[68:69] offset:20
	flat_load_dword v81, v[72:73] offset:20
	s_waitcnt vmcnt(0) lgkmcnt(0)
	v_add_f32_e32 v81, v64, v81
.Lmy_exp_196:
	s_andn2_saveexec_b64 s[18:19], s[18:19]
	s_cbranch_execz .Lmy_exp_198
	flat_load_dword v81, v[70:71] offset:20

; __global__ void __launch_bounds__(512, 2) fwd_kernel(KArgs a) {
;     ...
;                         const float* kf = KT + ((size_t)((ll * 16 + g) * 2 + 0) * 32) * 256 + i * 16 + j0; const float* kb = KT + ((size_t)((ll * 16 + g) * 2 + 1) * 32) * 256 + i * 16 + j0;
; #pragma unroll
;                         for (int j = 0; j < 8; ++j) v[j] = sp < s ? kf[(size_t)(s - sp) * 256 + j] : (sp > s ? kb[(size_t)(sp - s) * 256 + j] : kf[j] + kb[j]);
.Lmy_exp_200:
	s_waitcnt vmcnt(0) lgkmcnt(0)
	flat_load_dword v81, v[74:75] offset:20
.Lmy_exp_201:
	s_or_b64 exec, exec, s[58:59]
	s_and_saveexec_b64 s[58:59], s[36:37]
	s_xor_b64 s[58:59], exec, s[58:59]
	s_cbranch_execz .Lmy_exp_207
	s_and_saveexec_b64 s[18:19], vcc
	s_xor_b64 s[18:19], exec, s[18:19]
	s_cbranch_execz .Lmy_exp_204
	flat_load_dword v64, v[68:69] offset:24
	flat_load_dword v82, v[72:73] offset:24
	s_waitcnt vmcnt(0) lgkmcnt(0)
	v_add_f32_e32 v82, v64, v82
.Lmy_exp_204:
	s_andn2_saveexec_b64 s[18:19], s[18:19]
	s_cbranch_execz .Lmy_exp_206
	flat_load_dword v82, v[70:71] offset:24

; __device__ __forceinline__ unsigned cvt_pk_bf16(float lo, float hi) { unsigned r; asm volatile("v_cvt_pk_bf16_f32 %0, %1, %2" : "=v"(r) : "v"(lo), "v"(hi)); return r; }
; __device__ __forceinline__ unsigned xb_add(unsigned* p, unsigned v) { return __hip_atomic_fetch_add(p, v, __ATOMIC_RELAXED, __HIP_MEMORY_SCOPE_AGENT); }
; __device__ __forceinline__ void xcd_barrier(const XcdBarrier& b) {
;     asm volatile("s_waitcnt vmcnt(0)" ::: "memory");
;     __syncthreads();
;     if (threadIdx.x == 0) {
;         unsigned* bar = b.bar;
;         __builtin_amdgcn_s_waitcnt(0);
;         unsigned nloc = b.st[0], nx = b.st[1];
;         if (nloc == 0u) { xcd_barrier_complete(bar, b.x, nloc, nx); b.st[0] = nloc; b.st[1] = nx; }
;         const unsigned old = xb_add(&bar[XB_XSUB(b.x)], 1u);
; __global__ void __launch_bounds__(512, 2) fwd_kernel(KArgs a) {
;     ...
;                         const float* kf = KT + ((size_t)((ll * 16 + g) * 2 + 0) * 32) * 256 + i * 16 + j0; const float* kb = KT + ((size_t)((ll * 16 + g) * 2 + 1) * 32) * 256 + i * 16 + j0;
; #pragma unroll
;                         for (int j = 0; j < 8; ++j) v[j] = sp < s ? kf[(size_t)(s - sp) * 256 + j] : (sp > s ? kb[(size_t)(sp - s) * 256 + j] : kf[j] + kb[j]);
;                     } else { const int kk = k0 - 512, d = kk >> 7, ri = (kk >> 6) & 1, p0 = kk & 63, e = d == 0 ? s + 1 : 32 - s;
;                         const float* pw = POW + ((size_t)(((ll * 2 + d) * 16 + g) * 33 + e) * 64 + p0) * 2;
;                         const size_t ic = ((size_t)((ll * 2 + d) * 16 + g) * 16 + i) * 64 + p0;
; #pragma unroll
;                         for (int j = 0; j < 8; ++j) { const float cr = a.in[19][ic + j], ci = a.in[20][ic + j], pr = pw[2 * j], pi = pw[2 * j + 1];
;                             v[j] = ri == 0 ? cr * pr - ci * pi : -(cr * pi + ci * pr); }
;                     }
;                     u32x4 o; o.x = cvt_pk_bf16(v[0], v[1]); o.y = cvt_pk_bf16(v[2], v[3]); o.z = cvt_pk_bf16(v[4], v[5]); o.w = cvt_pk_bf16(v[6], v[7]);
;                     *(u32x4*)(BM2 + ((size_t)(ll * 16 + g) * 512 + n) * 768 + k0) = o;
.Lmy_exp_208:
	s_waitcnt vmcnt(0) lgkmcnt(0)
	flat_load_dword v82, v[74:75] offset:24
.Lmy_exp_209:
	s_or_b64 exec, exec, s[58:59]
	s_and_saveexec_b64 s[58:59], s[36:37]
	s_xor_b64 s[36:37], exec, s[58:59]
	s_cbranch_execz .Lmy_exp_215
	s_and_saveexec_b64 s[58:59], vcc
	s_xor_b64 s[58:59], exec, s[58:59]
	s_cbranch_execz .Lmy_exp_212
	flat_load_dword v64, v[68:69] offset:28
	s_nop 0
	flat_load_dword v68, v[72:73] offset:28
	s_waitcnt vmcnt(0) lgkmcnt(0)
	v_add_f32_e32 v83, v64, v68
.Lmy_exp_212:
	s_andn2_saveexec_b64 s[58:59], s[58:59]
	s_cbranch_execz .Lmy_exp_214
	flat_load_dword v83, v[70:71] offset:28
.Lmy_exp_214:
	s_or_b64 exec, exec, s[58:59]
	s_andn2_saveexec_b64 s[36:37], s[36:37]
	s_cbranch_execz .Lmy_exp_148
	s_branch .Lmy_exp_216
.Lmy_exp_215:
	s_andn2_saveexec_b64 s[36:37], s[36:37]
	s_cbranch_execz .Lmy_exp_148
.Lmy_exp_216:
	s_waitcnt vmcnt(0) lgkmcnt(0)
	flat_load_dword v83, v[74:75] offset:28
	s_branch .Lmy_exp_148
.Lmy_exp_217:
	s_or_b64 exec, exec, s[38:39]
	s_branch .Lmy_pad_Lmyexpskip
	s_nop 0
	s_nop 0
	s_nop 0
	s_nop 0
	s_nop 0
	s_nop 0
	s_nop 0
	s_nop 0
	s_nop 0
	s_nop 0
	s_nop 0
.Lmy_pad_Lmyexpskip:
.Lmy_exp_skip:
	s_waitcnt vmcnt(0)
	s_waitcnt vmcnt(0) lgkmcnt(0)
	s_barrier
	s_and_saveexec_b64 s[6:7], s[96:97]
	s_xor_b64 s[36:37], exec, s[6:7]
	s_cbranch_execz .LBB0_414
	v_readlane_b32 s1, v253, 44
	s_waitcnt vmcnt(0) expcnt(0) lgkmcnt(0)
	s_nop 0
	v_mov_b32_e32 v0, s1
	ds_read_b32 v3, v0
	v_readlane_b32 s1, v253, 45
	s_waitcnt lgkmcnt(0)
	v_cmp_ne_u32_e32 vcc, 0, v3
	v_mov_b32_e32 v0, s1
	ds_read_b32 v0, v0
	s_cbranch_vccnz .LBB0_381
	s_mov_b32 s1, 1
	s_branch .LBB0_369
